# GEMM epilogue: GATE and COMBINE tiles load their aux operands in batches ahead of the stores (counted vmcnt) instead of one load-wait-store round trip per 16 rows
# speedup vs baseline: 1.0044x; 1.0008x over previous
; __device__ __forceinline__ float bflo(unsigned w) { return __uint_as_float(w << 16); }
; __device__ __forceinline__ float bfhi(unsigned w) { return __uint_as_float(w & 0xffff0000u); }
; __device__ __forceinline__ float bflo(unsigned w) { return __uint_as_float(w << 16); }
; __device__ __forceinline__ float bfhi(unsigned w) { return __uint_as_float(w & 0xffff0000u); }
;     __device__ __forceinline__ void operator()(const f32x4 (&acc)[2][2][4][2], const Unit& u, int wr, int wc, int fr, int fq) const {
;     ...
;                         } else if (k == EK_GATE) {
;                             const u32x4e g = *(const u32x4e*)(aux1 + off);
;                             v0[0] *= bflo(g.x); v0[1] *= bfhi(g.x); v0[2] *= bflo(g.y); v0[3] *= bfhi(g.y);
;                             v1[0] *= bflo(g.z); v1[1] *= bfhi(g.z); v1[2] *= bflo(g.w); v1[3] *= bfhi(g.w);
;                         } else {
;                             const u32x4e y = *(const u32x4e*)(aux1 + off); const u32x4e g = *(const u32x4e*)(aux2 + off);
;                             v0[0] = bflo(y.x) + bflo(g.x) * v0[0]; v0[1] = bfhi(y.x) + bfhi(g.x) * v0[1]; v0[2] = bflo(y.y) + bflo(g.y) * v0[2]; v0[3] = bfhi(y.y) + bfhi(g.y) * v0[3];
;                             v1[0] = bflo(y.z) + bflo(g.z) * v1[0]; v1[1] = bfhi(y.z) + bfhi(g.z) * v1[1]; v1[2] = bflo(y.w) + bflo(g.w) * v1[2]; v1[3] = bfhi(y.w) + bfhi(g.w) * v1[3];
.Lepi_rs_done:
	s_cmp_eq_u32 s36, 4
	s_cbranch_scc1 .Lepi_gate_fast
	s_cmp_eq_u32 s36, 5
	s_cbranch_scc1 .Lepi_comb_fast
	s_and_b64 vcc, exec, s[30:31]
	s_cbranch_vccnz .LBB0_717
	s_cmp_lt_i32 s75, 15
	s_cbranch_scc1 .LBB0_720
	s_cmp_eq_u32 s75, 15
	s_cselect_b64 s[8:9], -1, 0
	s_cbranch_execz .LBB0_721
	s_branch .LBB0_722

; __device__ __forceinline__ unsigned cvt_pk_bf16(float lo, float hi) { unsigned r; asm volatile("v_cvt_pk_bf16_f32 %0, %1, %2" : "=v"(r) : "v"(lo), "v"(hi)); return r; }
; __device__ __forceinline__ float bflo(unsigned w) { return __uint_as_float(w << 16); }
; __device__ __forceinline__ float bfhi(unsigned w) { return __uint_as_float(w & 0xffff0000u); }
; __device__ __forceinline__ float bflo(unsigned w) { return __uint_as_float(w << 16); }
; __device__ __forceinline__ float bfhi(unsigned w) { return __uint_as_float(w & 0xffff0000u); }
;     __device__ __forceinline__ void operator()(const f32x4 (&acc)[2][2][4][2], const Unit& u, int wr, int wc, int fr, int fq) const {
;     ...
;                         } else if (k == EK_GATE) {
;                             const u32x4e g = *(const u32x4e*)(aux1 + off);
;                             v0[0] *= bflo(g.x); v0[1] *= bfhi(g.x); v0[2] *= bflo(g.y); v0[3] *= bfhi(g.y);
;                             v1[0] *= bflo(g.z); v1[1] *= bfhi(g.z); v1[2] *= bflo(g.w); v1[3] *= bfhi(g.w);
;     ...
;                         u32x4e w; w.x = cvt_pk_bf16(v0[0], v0[1]); w.y = cvt_pk_bf16(v0[2], v0[3]); w.z = cvt_pk_bf16(v1[0], v1[1]); w.w = cvt_pk_bf16(v1[2], v1[3]);
;                         *(u32x4e*)(base + off) = w;
.LBB0_966:
	v_cvt_pk_bf16_f32 v144, v146, v147
	v_cvt_pk_bf16_f32 v145, v152, v153
	s_nop 0
	v_cvt_pk_bf16_f32 v146, v150, v151
	v_cvt_pk_bf16_f32 v147, v156, v157
	global_store_dwordx4 v[148:149], v[144:147], off offset:256
	s_branch .LBB0_967
.Lepi_gate_fast:
	v_mad_i64_i32 v[148:149], s[8:9], s27, v140, v[142:143]
	s_lshl_b32 s16, s27, 5
	s_mov_b32 s17, 0
	s_mul_i32 s30, s27, 0xa0
	s_mov_b32 s31, 0
	v_lshl_add_u64 v[150:151], v[148:149], 1, s[40:41]
	v_lshl_add_u64 v[152:153], v[148:149], 1, s[20:21]
	global_load_dwordx4 v[176:179], v[152:153], off
	global_load_dwordx4 v[180:183], v[152:153], off offset:256
	v_lshl_add_u64 v[152:153], v[152:153], 0, s[16:17]
	global_load_dwordx4 v[184:187], v[152:153], off
	global_load_dwordx4 v[188:191], v[152:153], off offset:256
	v_lshl_add_u64 v[152:153], v[152:153], 0, s[16:17]
	global_load_dwordx4 v[192:195], v[152:153], off
	global_load_dwordx4 v[196:199], v[152:153], off offset:256
	v_lshl_add_u64 v[152:153], v[152:153], 0, s[16:17]
	global_load_dwordx4 v[200:203], v[152:153], off
	global_load_dwordx4 v[204:207], v[152:153], off offset:256
	v_lshl_add_u64 v[152:153], v[152:153], 0, s[30:31]
	s_waitcnt vmcnt(0)
	v_lshlrev_b32_e32 v146, 16, v176
	v_and_b32_e32 v147, 0xffff0000, v176
	v_pk_mul_f32 v[126:127], v[126:127], v[146:147]
	v_lshlrev_b32_e32 v146, 16, v177
	v_and_b32_e32 v147, 0xffff0000, v177
	v_pk_mul_f32 v[128:129], v[128:129], v[146:147]
	v_lshlrev_b32_e32 v146, 16, v178
	v_and_b32_e32 v147, 0xffff0000, v178
	v_pk_mul_f32 v[122:123], v[122:123], v[146:147]
	v_lshlrev_b32_e32 v146, 16, v179
	v_and_b32_e32 v147, 0xffff0000, v179
	v_pk_mul_f32 v[124:125], v[124:125], v[146:147]
	v_lshlrev_b32_e32 v146, 16, v180
	v_and_b32_e32 v147, 0xffff0000, v180
	v_pk_mul_f32 v[118:119], v[118:119], v[146:147]
	v_lshlrev_b32_e32 v146, 16, v181
	v_and_b32_e32 v147, 0xffff0000, v181
	v_pk_mul_f32 v[120:121], v[120:121], v[146:147]
	v_lshlrev_b32_e32 v146, 16, v182
	v_and_b32_e32 v147, 0xffff0000, v182
	v_pk_mul_f32 v[114:115], v[114:115], v[146:147]
	v_lshlrev_b32_e32 v146, 16, v183
	v_and_b32_e32 v147, 0xffff0000, v183
	v_pk_mul_f32 v[116:117], v[116:117], v[146:147]
	v_lshlrev_b32_e32 v146, 16, v184
	v_and_b32_e32 v147, 0xffff0000, v184
	v_pk_mul_f32 v[110:111], v[110:111], v[146:147]
	v_lshlrev_b32_e32 v146, 16, v185
	v_and_b32_e32 v147, 0xffff0000, v185
	v_pk_mul_f32 v[112:113], v[112:113], v[146:147]
	v_lshlrev_b32_e32 v146, 16, v186
	v_and_b32_e32 v147, 0xffff0000, v186
	v_pk_mul_f32 v[106:107], v[106:107], v[146:147]
	v_lshlrev_b32_e32 v146, 16, v187
	v_and_b32_e32 v147, 0xffff0000, v187
	v_pk_mul_f32 v[108:109], v[108:109], v[146:147]
	v_lshlrev_b32_e32 v146, 16, v188
	v_and_b32_e32 v147, 0xffff0000, v188
	v_pk_mul_f32 v[102:103], v[102:103], v[146:147]
	v_lshlrev_b32_e32 v146, 16, v189
	v_and_b32_e32 v147, 0xffff0000, v189
	v_pk_mul_f32 v[104:105], v[104:105], v[146:147]
	v_lshlrev_b32_e32 v146, 16, v190
	v_and_b32_e32 v147, 0xffff0000, v190
	v_pk_mul_f32 v[98:99], v[98:99], v[146:147]
	v_lshlrev_b32_e32 v146, 16, v191
	v_and_b32_e32 v147, 0xffff0000, v191
	v_pk_mul_f32 v[100:101], v[100:101], v[146:147]
	v_lshlrev_b32_e32 v146, 16, v192
	v_and_b32_e32 v147, 0xffff0000, v192
	v_pk_mul_f32 v[94:95], v[94:95], v[146:147]
	v_lshlrev_b32_e32 v146, 16, v193
	v_and_b32_e32 v147, 0xffff0000, v193
	v_pk_mul_f32 v[96:97], v[96:97], v[146:147]
	v_lshlrev_b32_e32 v146, 16, v194
	v_and_b32_e32 v147, 0xffff0000, v194
	v_pk_mul_f32 v[90:91], v[90:91], v[146:147]
	v_lshlrev_b32_e32 v146, 16, v195
	v_and_b32_e32 v147, 0xffff0000, v195
	v_pk_mul_f32 v[92:93], v[92:93], v[146:147]
	v_lshlrev_b32_e32 v146, 16, v196
	v_and_b32_e32 v147, 0xffff0000, v196
	v_pk_mul_f32 v[86:87], v[86:87], v[146:147]
	v_lshlrev_b32_e32 v146, 16, v197
	v_and_b32_e32 v147, 0xffff0000, v197
	v_pk_mul_f32 v[88:89], v[88:89], v[146:147]
	v_lshlrev_b32_e32 v146, 16, v198
	v_and_b32_e32 v147, 0xffff0000, v198
	v_pk_mul_f32 v[82:83], v[82:83], v[146:147]
	v_lshlrev_b32_e32 v146, 16, v199
	v_and_b32_e32 v147, 0xffff0000, v199
	v_pk_mul_f32 v[84:85], v[84:85], v[146:147]
	v_lshlrev_b32_e32 v146, 16, v200
	v_and_b32_e32 v147, 0xffff0000, v200
	v_pk_mul_f32 v[78:79], v[78:79], v[146:147]
	v_lshlrev_b32_e32 v146, 16, v201
	v_and_b32_e32 v147, 0xffff0000, v201
	v_pk_mul_f32 v[80:81], v[80:81], v[146:147]
	v_lshlrev_b32_e32 v146, 16, v202
	v_and_b32_e32 v147, 0xffff0000, v202
	v_pk_mul_f32 v[74:75], v[74:75], v[146:147]
	v_lshlrev_b32_e32 v146, 16, v203
	v_and_b32_e32 v147, 0xffff0000, v203
	v_pk_mul_f32 v[76:77], v[76:77], v[146:147]
	v_lshlrev_b32_e32 v146, 16, v204
	v_and_b32_e32 v147, 0xffff0000, v204
	v_pk_mul_f32 v[70:71], v[70:71], v[146:147]
	v_lshlrev_b32_e32 v146, 16, v205
	v_and_b32_e32 v147, 0xffff0000, v205
	v_pk_mul_f32 v[72:73], v[72:73], v[146:147]
	v_lshlrev_b32_e32 v146, 16, v206
	v_and_b32_e32 v147, 0xffff0000, v206
	v_pk_mul_f32 v[66:67], v[66:67], v[146:147]
	v_lshlrev_b32_e32 v146, 16, v207
	v_and_b32_e32 v147, 0xffff0000, v207
	v_pk_mul_f32 v[68:69], v[68:69], v[146:147]
	global_load_dwordx4 v[176:179], v[152:153], off
	global_load_dwordx4 v[180:183], v[152:153], off offset:256
	v_lshl_add_u64 v[152:153], v[152:153], 0, s[16:17]
	global_load_dwordx4 v[184:187], v[152:153], off
	global_load_dwordx4 v[188:191], v[152:153], off offset:256
	v_lshl_add_u64 v[152:153], v[152:153], 0, s[16:17]
	global_load_dwordx4 v[192:195], v[152:153], off
	global_load_dwordx4 v[196:199], v[152:153], off offset:256
	v_lshl_add_u64 v[152:153], v[152:153], 0, s[16:17]
	global_load_dwordx4 v[200:203], v[152:153], off
	global_load_dwordx4 v[204:207], v[152:153], off offset:256
	v_cvt_pk_bf16_f32 v172, v126, v127
	v_cvt_pk_bf16_f32 v173, v128, v129
; __device__ __forceinline__ unsigned cvt_pk_bf16(float lo, float hi) { unsigned r; asm volatile("v_cvt_pk_bf16_f32 %0, %1, %2" : "=v"(r) : "v"(lo), "v"(hi)); return r; }
; __device__ __forceinline__ float bflo(unsigned w) { return __uint_as_float(w << 16); }
; __device__ __forceinline__ float bfhi(unsigned w) { return __uint_as_float(w & 0xffff0000u); }
; __device__ __forceinline__ float bflo(unsigned w) { return __uint_as_float(w << 16); }
; __device__ __forceinline__ float bfhi(unsigned w) { return __uint_as_float(w & 0xffff0000u); }
;     __device__ __forceinline__ void operator()(const f32x4 (&acc)[2][2][4][2], const Unit& u, int wr, int wc, int fr, int fq) const {
;     ...
;                         } else if (k == EK_GATE) {
;                             const u32x4e g = *(const u32x4e*)(aux1 + off);
;                             v0[0] *= bflo(g.x); v0[1] *= bfhi(g.x); v0[2] *= bflo(g.y); v0[3] *= bfhi(g.y);
;                             v1[0] *= bflo(g.z); v1[1] *= bfhi(g.z); v1[2] *= bflo(g.w); v1[3] *= bfhi(g.w);
;     ...
;                         u32x4e w; w.x = cvt_pk_bf16(v0[0], v0[1]); w.y = cvt_pk_bf16(v0[2], v0[3]); w.z = cvt_pk_bf16(v1[0], v1[1]); w.w = cvt_pk_bf16(v1[2], v1[3]);
;                         *(u32x4e*)(base + off) = w;
	v_cvt_pk_bf16_f32 v174, v122, v123
	v_cvt_pk_bf16_f32 v175, v124, v125
	global_store_dwordx4 v[150:151], v[172:175], off
	v_cvt_pk_bf16_f32 v156, v118, v119
	v_cvt_pk_bf16_f32 v157, v120, v121
	v_cvt_pk_bf16_f32 v158, v114, v115
	v_cvt_pk_bf16_f32 v159, v116, v117
	global_store_dwordx4 v[150:151], v[156:159], off offset:256
	v_lshl_add_u64 v[150:151], v[150:151], 0, s[16:17]
	v_cvt_pk_bf16_f32 v172, v110, v111
	v_cvt_pk_bf16_f32 v173, v112, v113
	v_cvt_pk_bf16_f32 v174, v106, v107
	v_cvt_pk_bf16_f32 v175, v108, v109
	global_store_dwordx4 v[150:151], v[172:175], off
	v_cvt_pk_bf16_f32 v156, v102, v103
	v_cvt_pk_bf16_f32 v157, v104, v105
	v_cvt_pk_bf16_f32 v158, v98, v99
	v_cvt_pk_bf16_f32 v159, v100, v101
	global_store_dwordx4 v[150:151], v[156:159], off offset:256
	v_lshl_add_u64 v[150:151], v[150:151], 0, s[16:17]
	v_cvt_pk_bf16_f32 v172, v94, v95
	v_cvt_pk_bf16_f32 v173, v96, v97
	v_cvt_pk_bf16_f32 v174, v90, v91
	v_cvt_pk_bf16_f32 v175, v92, v93
	global_store_dwordx4 v[150:151], v[172:175], off
	v_cvt_pk_bf16_f32 v156, v86, v87
	v_cvt_pk_bf16_f32 v157, v88, v89
	v_cvt_pk_bf16_f32 v158, v82, v83
	v_cvt_pk_bf16_f32 v159, v84, v85
	global_store_dwordx4 v[150:151], v[156:159], off offset:256
	v_lshl_add_u64 v[150:151], v[150:151], 0, s[16:17]
	v_cvt_pk_bf16_f32 v172, v78, v79
	v_cvt_pk_bf16_f32 v173, v80, v81
	v_cvt_pk_bf16_f32 v174, v74, v75
	v_cvt_pk_bf16_f32 v175, v76, v77
	global_store_dwordx4 v[150:151], v[172:175], off
	v_cvt_pk_bf16_f32 v156, v70, v71
	v_cvt_pk_bf16_f32 v157, v72, v73
	v_cvt_pk_bf16_f32 v158, v66, v67
	v_cvt_pk_bf16_f32 v159, v68, v69
	global_store_dwordx4 v[150:151], v[156:159], off offset:256
	v_lshl_add_u64 v[150:151], v[150:151], 0, s[30:31]
	s_waitcnt vmcnt(8)
	v_lshlrev_b32_e32 v146, 16, v176
	v_and_b32_e32 v147, 0xffff0000, v176
	v_pk_mul_f32 v[60:61], v[60:61], v[146:147]
	v_lshlrev_b32_e32 v146, 16, v177
	v_and_b32_e32 v147, 0xffff0000, v177
	v_pk_mul_f32 v[62:63], v[62:63], v[146:147]
	v_lshlrev_b32_e32 v146, 16, v178
	v_and_b32_e32 v147, 0xffff0000, v178
	v_pk_mul_f32 v[56:57], v[56:57], v[146:147]
	v_lshlrev_b32_e32 v146, 16, v179
	v_and_b32_e32 v147, 0xffff0000, v179
	v_pk_mul_f32 v[58:59], v[58:59], v[146:147]
	v_lshlrev_b32_e32 v146, 16, v180
	v_and_b32_e32 v147, 0xffff0000, v180
	v_pk_mul_f32 v[52:53], v[52:53], v[146:147]
	v_lshlrev_b32_e32 v146, 16, v181
	v_and_b32_e32 v147, 0xffff0000, v181
	v_pk_mul_f32 v[54:55], v[54:55], v[146:147]
	v_lshlrev_b32_e32 v146, 16, v182
	v_and_b32_e32 v147, 0xffff0000, v182
	v_pk_mul_f32 v[48:49], v[48:49], v[146:147]
	v_lshlrev_b32_e32 v146, 16, v183
	v_and_b32_e32 v147, 0xffff0000, v183
	v_pk_mul_f32 v[50:51], v[50:51], v[146:147]
	v_lshlrev_b32_e32 v146, 16, v184
	v_and_b32_e32 v147, 0xffff0000, v184
	v_pk_mul_f32 v[44:45], v[44:45], v[146:147]
	v_lshlrev_b32_e32 v146, 16, v185
	v_and_b32_e32 v147, 0xffff0000, v185
	v_pk_mul_f32 v[46:47], v[46:47], v[146:147]
	v_lshlrev_b32_e32 v146, 16, v186
	v_and_b32_e32 v147, 0xffff0000, v186
	v_pk_mul_f32 v[40:41], v[40:41], v[146:147]
	v_lshlrev_b32_e32 v146, 16, v187
	v_and_b32_e32 v147, 0xffff0000, v187
	v_pk_mul_f32 v[42:43], v[42:43], v[146:147]
	v_lshlrev_b32_e32 v146, 16, v188
	v_and_b32_e32 v147, 0xffff0000, v188
	v_pk_mul_f32 v[36:37], v[36:37], v[146:147]
	v_lshlrev_b32_e32 v146, 16, v189
	v_and_b32_e32 v147, 0xffff0000, v189
	v_pk_mul_f32 v[38:39], v[38:39], v[146:147]
	v_lshlrev_b32_e32 v146, 16, v190
	v_and_b32_e32 v147, 0xffff0000, v190
	v_pk_mul_f32 v[32:33], v[32:33], v[146:147]
	v_lshlrev_b32_e32 v146, 16, v191
	v_and_b32_e32 v147, 0xffff0000, v191
	v_pk_mul_f32 v[34:35], v[34:35], v[146:147]
	v_lshlrev_b32_e32 v146, 16, v192
	v_and_b32_e32 v147, 0xffff0000, v192
	v_pk_mul_f32 v[28:29], v[28:29], v[146:147]
	v_lshlrev_b32_e32 v146, 16, v193
	v_and_b32_e32 v147, 0xffff0000, v193
	v_pk_mul_f32 v[30:31], v[30:31], v[146:147]
	v_lshlrev_b32_e32 v146, 16, v194
	v_and_b32_e32 v147, 0xffff0000, v194
	v_pk_mul_f32 v[24:25], v[24:25], v[146:147]
	v_lshlrev_b32_e32 v146, 16, v195
	v_and_b32_e32 v147, 0xffff0000, v195
	v_pk_mul_f32 v[26:27], v[26:27], v[146:147]
	v_lshlrev_b32_e32 v146, 16, v196
	v_and_b32_e32 v147, 0xffff0000, v196
	v_pk_mul_f32 v[20:21], v[20:21], v[146:147]
	v_lshlrev_b32_e32 v146, 16, v197
	v_and_b32_e32 v147, 0xffff0000, v197
	v_pk_mul_f32 v[22:23], v[22:23], v[146:147]
	v_lshlrev_b32_e32 v146, 16, v198
	v_and_b32_e32 v147, 0xffff0000, v198
	v_pk_mul_f32 v[16:17], v[16:17], v[146:147]
	v_lshlrev_b32_e32 v146, 16, v199
	v_and_b32_e32 v147, 0xffff0000, v199
	v_pk_mul_f32 v[18:19], v[18:19], v[146:147]
	v_lshlrev_b32_e32 v146, 16, v200
	v_and_b32_e32 v147, 0xffff0000, v200
	v_pk_mul_f32 v[12:13], v[12:13], v[146:147]
	v_lshlrev_b32_e32 v146, 16, v201
	v_and_b32_e32 v147, 0xffff0000, v201
	v_pk_mul_f32 v[14:15], v[14:15], v[146:147]
	v_lshlrev_b32_e32 v146, 16, v202
	v_and_b32_e32 v147, 0xffff0000, v202
	v_pk_mul_f32 v[8:9], v[8:9], v[146:147]
	v_lshlrev_b32_e32 v146, 16, v203
	v_and_b32_e32 v147, 0xffff0000, v203
	v_pk_mul_f32 v[10:11], v[10:11], v[146:147]
	v_lshlrev_b32_e32 v146, 16, v204
	v_and_b32_e32 v147, 0xffff0000, v204
	v_pk_mul_f32 v[4:5], v[4:5], v[146:147]
	v_lshlrev_b32_e32 v146, 16, v205
	v_and_b32_e32 v147, 0xffff0000, v205
	v_pk_mul_f32 v[6:7], v[6:7], v[146:147]
	v_lshlrev_b32_e32 v146, 16, v206
	v_and_b32_e32 v147, 0xffff0000, v206
	v_pk_mul_f32 v[0:1], v[0:1], v[146:147]
	v_lshlrev_b32_e32 v146, 16, v207
	v_and_b32_e32 v147, 0xffff0000, v207
	v_pk_mul_f32 v[2:3], v[2:3], v[146:147]
	v_cvt_pk_bf16_f32 v172, v60, v61
	v_cvt_pk_bf16_f32 v173, v62, v63
	v_cvt_pk_bf16_f32 v174, v56, v57
	v_cvt_pk_bf16_f32 v175, v58, v59
	global_store_dwordx4 v[150:151], v[172:175], off
; __device__ __forceinline__ unsigned cvt_pk_bf16(float lo, float hi) { unsigned r; asm volatile("v_cvt_pk_bf16_f32 %0, %1, %2" : "=v"(r) : "v"(lo), "v"(hi)); return r; }
; __device__ __forceinline__ float bflo(unsigned w) { return __uint_as_float(w << 16); }
; __device__ __forceinline__ float bfhi(unsigned w) { return __uint_as_float(w & 0xffff0000u); }
; __device__ __forceinline__ float bflo(unsigned w) { return __uint_as_float(w << 16); }
; __device__ __forceinline__ float bfhi(unsigned w) { return __uint_as_float(w & 0xffff0000u); }
;     __device__ __forceinline__ void operator()(const f32x4 (&acc)[2][2][4][2], const Unit& u, int wr, int wc, int fr, int fq) const {
;     ...
;                         } else {
;                             const u32x4e y = *(const u32x4e*)(aux1 + off); const u32x4e g = *(const u32x4e*)(aux2 + off);
;                             v0[0] = bflo(y.x) + bflo(g.x) * v0[0]; v0[1] = bfhi(y.x) + bfhi(g.x) * v0[1]; v0[2] = bflo(y.y) + bflo(g.y) * v0[2]; v0[3] = bfhi(y.y) + bfhi(g.y) * v0[3];
;                             v1[0] = bflo(y.z) + bflo(g.z) * v1[0]; v1[1] = bfhi(y.z) + bfhi(g.z) * v1[1]; v1[2] = bflo(y.w) + bflo(g.w) * v1[2]; v1[3] = bfhi(y.w) + bfhi(g.w) * v1[3];
;                         }
;                         u32x4e w; w.x = cvt_pk_bf16(v0[0], v0[1]); w.y = cvt_pk_bf16(v0[2], v0[3]); w.z = cvt_pk_bf16(v1[0], v1[1]); w.w = cvt_pk_bf16(v1[2], v1[3]);
;                         *(u32x4e*)(base + off) = w;
	v_cvt_pk_bf16_f32 v156, v52, v53
	v_cvt_pk_bf16_f32 v157, v54, v55
	v_cvt_pk_bf16_f32 v158, v48, v49
	v_cvt_pk_bf16_f32 v159, v50, v51
	global_store_dwordx4 v[150:151], v[156:159], off offset:256
	v_lshl_add_u64 v[150:151], v[150:151], 0, s[16:17]
	v_cvt_pk_bf16_f32 v172, v44, v45
	v_cvt_pk_bf16_f32 v173, v46, v47
	v_cvt_pk_bf16_f32 v174, v40, v41
	v_cvt_pk_bf16_f32 v175, v42, v43
	global_store_dwordx4 v[150:151], v[172:175], off
	v_cvt_pk_bf16_f32 v156, v36, v37
	v_cvt_pk_bf16_f32 v157, v38, v39
	v_cvt_pk_bf16_f32 v158, v32, v33
	v_cvt_pk_bf16_f32 v159, v34, v35
	global_store_dwordx4 v[150:151], v[156:159], off offset:256
	v_lshl_add_u64 v[150:151], v[150:151], 0, s[16:17]
	v_cvt_pk_bf16_f32 v172, v28, v29
	v_cvt_pk_bf16_f32 v173, v30, v31
	v_cvt_pk_bf16_f32 v174, v24, v25
	v_cvt_pk_bf16_f32 v175, v26, v27
	global_store_dwordx4 v[150:151], v[172:175], off
	v_cvt_pk_bf16_f32 v156, v20, v21
	v_cvt_pk_bf16_f32 v157, v22, v23
	v_cvt_pk_bf16_f32 v158, v16, v17
	v_cvt_pk_bf16_f32 v159, v18, v19
	global_store_dwordx4 v[150:151], v[156:159], off offset:256
	v_lshl_add_u64 v[150:151], v[150:151], 0, s[16:17]
	v_cvt_pk_bf16_f32 v172, v12, v13
	v_cvt_pk_bf16_f32 v173, v14, v15
	v_cvt_pk_bf16_f32 v174, v8, v9
	v_cvt_pk_bf16_f32 v175, v10, v11
	global_store_dwordx4 v[150:151], v[172:175], off
	v_cvt_pk_bf16_f32 v156, v4, v5
	v_cvt_pk_bf16_f32 v157, v6, v7
	v_cvt_pk_bf16_f32 v158, v0, v1
	v_cvt_pk_bf16_f32 v159, v2, v3
	global_store_dwordx4 v[150:151], v[156:159], off offset:256
	s_branch .LBB0_967
.Lepi_comb_fast:
	v_mad_i64_i32 v[148:149], s[8:9], s27, v140, v[142:143]
	s_lshl_b32 s16, s27, 5
	s_mov_b32 s17, 0
	s_mul_i32 s30, s27, 0xa0
	s_mov_b32 s31, 0
	v_lshl_add_u64 v[150:151], v[148:149], 1, s[40:41]
	v_lshl_add_u64 v[152:153], v[148:149], 1, s[20:21]
	v_lshl_add_u64 v[154:155], v[148:149], 1, s[18:19]
	global_load_dwordx4 v[176:179], v[152:153], off
	global_load_dwordx4 v[192:195], v[154:155], off
	global_load_dwordx4 v[180:183], v[152:153], off offset:256
	global_load_dwordx4 v[196:199], v[154:155], off offset:256
	v_lshl_add_u64 v[152:153], v[152:153], 0, s[16:17]
	v_lshl_add_u64 v[154:155], v[154:155], 0, s[16:17]
	global_load_dwordx4 v[184:187], v[152:153], off
	global_load_dwordx4 v[200:203], v[154:155], off
	global_load_dwordx4 v[188:191], v[152:153], off offset:256
	global_load_dwordx4 v[204:207], v[154:155], off offset:256
	v_lshl_add_u64 v[152:153], v[152:153], 0, s[16:17]
	v_lshl_add_u64 v[154:155], v[154:155], 0, s[16:17]
	s_waitcnt vmcnt(0)
	v_lshlrev_b32_e32 v146, 16, v176
	v_and_b32_e32 v147, 0xffff0000, v176
	v_lshlrev_b32_e32 v144, 16, v192
	v_and_b32_e32 v145, 0xffff0000, v192
	v_pk_fma_f32 v[126:127], v[126:127], v[144:145], v[146:147]
	v_lshlrev_b32_e32 v146, 16, v177
	v_and_b32_e32 v147, 0xffff0000, v177
	v_lshlrev_b32_e32 v144, 16, v193
	v_and_b32_e32 v145, 0xffff0000, v193
	v_pk_fma_f32 v[128:129], v[128:129], v[144:145], v[146:147]
	v_lshlrev_b32_e32 v146, 16, v178
	v_and_b32_e32 v147, 0xffff0000, v178
	v_lshlrev_b32_e32 v144, 16, v194
	v_and_b32_e32 v145, 0xffff0000, v194
	v_pk_fma_f32 v[122:123], v[122:123], v[144:145], v[146:147]
	v_lshlrev_b32_e32 v146, 16, v179
	v_and_b32_e32 v147, 0xffff0000, v179
	v_lshlrev_b32_e32 v144, 16, v195
	v_and_b32_e32 v145, 0xffff0000, v195
	v_pk_fma_f32 v[124:125], v[124:125], v[144:145], v[146:147]
	v_lshlrev_b32_e32 v146, 16, v180
	v_and_b32_e32 v147, 0xffff0000, v180
	v_lshlrev_b32_e32 v144, 16, v196
	v_and_b32_e32 v145, 0xffff0000, v196
	v_pk_fma_f32 v[118:119], v[118:119], v[144:145], v[146:147]
	v_lshlrev_b32_e32 v146, 16, v181
	v_and_b32_e32 v147, 0xffff0000, v181
	v_lshlrev_b32_e32 v144, 16, v197
	v_and_b32_e32 v145, 0xffff0000, v197
	v_pk_fma_f32 v[120:121], v[120:121], v[144:145], v[146:147]
	v_lshlrev_b32_e32 v146, 16, v182
	v_and_b32_e32 v147, 0xffff0000, v182
	v_lshlrev_b32_e32 v144, 16, v198
	v_and_b32_e32 v145, 0xffff0000, v198
	v_pk_fma_f32 v[114:115], v[114:115], v[144:145], v[146:147]
	v_lshlrev_b32_e32 v146, 16, v183
	v_and_b32_e32 v147, 0xffff0000, v183
	v_lshlrev_b32_e32 v144, 16, v199
	v_and_b32_e32 v145, 0xffff0000, v199
	v_pk_fma_f32 v[116:117], v[116:117], v[144:145], v[146:147]
	v_lshlrev_b32_e32 v146, 16, v184
	v_and_b32_e32 v147, 0xffff0000, v184
	v_lshlrev_b32_e32 v144, 16, v200
	v_and_b32_e32 v145, 0xffff0000, v200
	v_pk_fma_f32 v[110:111], v[110:111], v[144:145], v[146:147]
	v_lshlrev_b32_e32 v146, 16, v185
	v_and_b32_e32 v147, 0xffff0000, v185
	v_lshlrev_b32_e32 v144, 16, v201
	v_and_b32_e32 v145, 0xffff0000, v201
	v_pk_fma_f32 v[112:113], v[112:113], v[144:145], v[146:147]
	v_lshlrev_b32_e32 v146, 16, v186
	v_and_b32_e32 v147, 0xffff0000, v186
	v_lshlrev_b32_e32 v144, 16, v202
	v_and_b32_e32 v145, 0xffff0000, v202
	v_pk_fma_f32 v[106:107], v[106:107], v[144:145], v[146:147]
	v_lshlrev_b32_e32 v146, 16, v187
	v_and_b32_e32 v147, 0xffff0000, v187
	v_lshlrev_b32_e32 v144, 16, v203
	v_and_b32_e32 v145, 0xffff0000, v203
	v_pk_fma_f32 v[108:109], v[108:109], v[144:145], v[146:147]
	v_lshlrev_b32_e32 v146, 16, v188
	v_and_b32_e32 v147, 0xffff0000, v188
	v_lshlrev_b32_e32 v144, 16, v204
	v_and_b32_e32 v145, 0xffff0000, v204
	v_pk_fma_f32 v[102:103], v[102:103], v[144:145], v[146:147]
	v_lshlrev_b32_e32 v146, 16, v189
	v_and_b32_e32 v147, 0xffff0000, v189
	v_lshlrev_b32_e32 v144, 16, v205
	v_and_b32_e32 v145, 0xffff0000, v205
	v_pk_fma_f32 v[104:105], v[104:105], v[144:145], v[146:147]
	v_lshlrev_b32_e32 v146, 16, v190
	v_and_b32_e32 v147, 0xffff0000, v190
	v_lshlrev_b32_e32 v144, 16, v206
	v_and_b32_e32 v145, 0xffff0000, v206
	v_pk_fma_f32 v[98:99], v[98:99], v[144:145], v[146:147]
	v_lshlrev_b32_e32 v146, 16, v191
	v_and_b32_e32 v147, 0xffff0000, v191
; __device__ __forceinline__ unsigned cvt_pk_bf16(float lo, float hi) { unsigned r; asm volatile("v_cvt_pk_bf16_f32 %0, %1, %2" : "=v"(r) : "v"(lo), "v"(hi)); return r; }
; __device__ __forceinline__ float bflo(unsigned w) { return __uint_as_float(w << 16); }
; __device__ __forceinline__ float bfhi(unsigned w) { return __uint_as_float(w & 0xffff0000u); }
; __device__ __forceinline__ float bflo(unsigned w) { return __uint_as_float(w << 16); }
; __device__ __forceinline__ float bfhi(unsigned w) { return __uint_as_float(w & 0xffff0000u); }
;     __device__ __forceinline__ void operator()(const f32x4 (&acc)[2][2][4][2], const Unit& u, int wr, int wc, int fr, int fq) const {
;     ...
;                         } else {
;                             const u32x4e y = *(const u32x4e*)(aux1 + off); const u32x4e g = *(const u32x4e*)(aux2 + off);
;                             v0[0] = bflo(y.x) + bflo(g.x) * v0[0]; v0[1] = bfhi(y.x) + bfhi(g.x) * v0[1]; v0[2] = bflo(y.y) + bflo(g.y) * v0[2]; v0[3] = bfhi(y.y) + bfhi(g.y) * v0[3];
;                             v1[0] = bflo(y.z) + bflo(g.z) * v1[0]; v1[1] = bfhi(y.z) + bfhi(g.z) * v1[1]; v1[2] = bflo(y.w) + bflo(g.w) * v1[2]; v1[3] = bfhi(y.w) + bfhi(g.w) * v1[3];
;                         }
;                         u32x4e w; w.x = cvt_pk_bf16(v0[0], v0[1]); w.y = cvt_pk_bf16(v0[2], v0[3]); w.z = cvt_pk_bf16(v1[0], v1[1]); w.w = cvt_pk_bf16(v1[2], v1[3]);
;                         *(u32x4e*)(base + off) = w;
	v_lshlrev_b32_e32 v144, 16, v207
	v_and_b32_e32 v145, 0xffff0000, v207
	v_pk_fma_f32 v[100:101], v[100:101], v[144:145], v[146:147]
	global_load_dwordx4 v[176:179], v[152:153], off
	global_load_dwordx4 v[192:195], v[154:155], off
	global_load_dwordx4 v[180:183], v[152:153], off offset:256
	global_load_dwordx4 v[196:199], v[154:155], off offset:256
	v_lshl_add_u64 v[152:153], v[152:153], 0, s[16:17]
	v_lshl_add_u64 v[154:155], v[154:155], 0, s[16:17]
	global_load_dwordx4 v[184:187], v[152:153], off
	global_load_dwordx4 v[200:203], v[154:155], off
	global_load_dwordx4 v[188:191], v[152:153], off offset:256
	global_load_dwordx4 v[204:207], v[154:155], off offset:256
	v_lshl_add_u64 v[152:153], v[152:153], 0, s[30:31]
	v_lshl_add_u64 v[154:155], v[154:155], 0, s[30:31]
	v_cvt_pk_bf16_f32 v172, v126, v127
	v_cvt_pk_bf16_f32 v173, v128, v129
	v_cvt_pk_bf16_f32 v174, v122, v123
	v_cvt_pk_bf16_f32 v175, v124, v125
	global_store_dwordx4 v[150:151], v[172:175], off
	v_cvt_pk_bf16_f32 v156, v118, v119
	v_cvt_pk_bf16_f32 v157, v120, v121
	v_cvt_pk_bf16_f32 v158, v114, v115
	v_cvt_pk_bf16_f32 v159, v116, v117
	global_store_dwordx4 v[150:151], v[156:159], off offset:256
	v_lshl_add_u64 v[150:151], v[150:151], 0, s[16:17]
	v_cvt_pk_bf16_f32 v172, v110, v111
	v_cvt_pk_bf16_f32 v173, v112, v113
	v_cvt_pk_bf16_f32 v174, v106, v107
	v_cvt_pk_bf16_f32 v175, v108, v109
	global_store_dwordx4 v[150:151], v[172:175], off
	v_cvt_pk_bf16_f32 v156, v102, v103
	v_cvt_pk_bf16_f32 v157, v104, v105
	v_cvt_pk_bf16_f32 v158, v98, v99
	v_cvt_pk_bf16_f32 v159, v100, v101
	global_store_dwordx4 v[150:151], v[156:159], off offset:256
	v_lshl_add_u64 v[150:151], v[150:151], 0, s[16:17]
	s_waitcnt vmcnt(4)
	v_lshlrev_b32_e32 v146, 16, v176
	v_and_b32_e32 v147, 0xffff0000, v176
	v_lshlrev_b32_e32 v144, 16, v192
	v_and_b32_e32 v145, 0xffff0000, v192
	v_pk_fma_f32 v[94:95], v[94:95], v[144:145], v[146:147]
	v_lshlrev_b32_e32 v146, 16, v177
	v_and_b32_e32 v147, 0xffff0000, v177
	v_lshlrev_b32_e32 v144, 16, v193
	v_and_b32_e32 v145, 0xffff0000, v193
	v_pk_fma_f32 v[96:97], v[96:97], v[144:145], v[146:147]
	v_lshlrev_b32_e32 v146, 16, v178
	v_and_b32_e32 v147, 0xffff0000, v178
	v_lshlrev_b32_e32 v144, 16, v194
	v_and_b32_e32 v145, 0xffff0000, v194
	v_pk_fma_f32 v[90:91], v[90:91], v[144:145], v[146:147]
	v_lshlrev_b32_e32 v146, 16, v179
	v_and_b32_e32 v147, 0xffff0000, v179
	v_lshlrev_b32_e32 v144, 16, v195
	v_and_b32_e32 v145, 0xffff0000, v195
	v_pk_fma_f32 v[92:93], v[92:93], v[144:145], v[146:147]
	v_lshlrev_b32_e32 v146, 16, v180
	v_and_b32_e32 v147, 0xffff0000, v180
	v_lshlrev_b32_e32 v144, 16, v196
	v_and_b32_e32 v145, 0xffff0000, v196
	v_pk_fma_f32 v[86:87], v[86:87], v[144:145], v[146:147]
	v_lshlrev_b32_e32 v146, 16, v181
	v_and_b32_e32 v147, 0xffff0000, v181
	v_lshlrev_b32_e32 v144, 16, v197
	v_and_b32_e32 v145, 0xffff0000, v197
	v_pk_fma_f32 v[88:89], v[88:89], v[144:145], v[146:147]
	v_lshlrev_b32_e32 v146, 16, v182
	v_and_b32_e32 v147, 0xffff0000, v182
	v_lshlrev_b32_e32 v144, 16, v198
	v_and_b32_e32 v145, 0xffff0000, v198
	v_pk_fma_f32 v[82:83], v[82:83], v[144:145], v[146:147]
	v_lshlrev_b32_e32 v146, 16, v183
	v_and_b32_e32 v147, 0xffff0000, v183
	v_lshlrev_b32_e32 v144, 16, v199
	v_and_b32_e32 v145, 0xffff0000, v199
	v_pk_fma_f32 v[84:85], v[84:85], v[144:145], v[146:147]
	v_lshlrev_b32_e32 v146, 16, v184
	v_and_b32_e32 v147, 0xffff0000, v184
	v_lshlrev_b32_e32 v144, 16, v200
	v_and_b32_e32 v145, 0xffff0000, v200
	v_pk_fma_f32 v[78:79], v[78:79], v[144:145], v[146:147]
	v_lshlrev_b32_e32 v146, 16, v185
	v_and_b32_e32 v147, 0xffff0000, v185
	v_lshlrev_b32_e32 v144, 16, v201
	v_and_b32_e32 v145, 0xffff0000, v201
	v_pk_fma_f32 v[80:81], v[80:81], v[144:145], v[146:147]
	v_lshlrev_b32_e32 v146, 16, v186
	v_and_b32_e32 v147, 0xffff0000, v186
	v_lshlrev_b32_e32 v144, 16, v202
	v_and_b32_e32 v145, 0xffff0000, v202
	v_pk_fma_f32 v[74:75], v[74:75], v[144:145], v[146:147]
	v_lshlrev_b32_e32 v146, 16, v187
	v_and_b32_e32 v147, 0xffff0000, v187
	v_lshlrev_b32_e32 v144, 16, v203
	v_and_b32_e32 v145, 0xffff0000, v203
	v_pk_fma_f32 v[76:77], v[76:77], v[144:145], v[146:147]
	v_lshlrev_b32_e32 v146, 16, v188
	v_and_b32_e32 v147, 0xffff0000, v188
	v_lshlrev_b32_e32 v144, 16, v204
	v_and_b32_e32 v145, 0xffff0000, v204
	v_pk_fma_f32 v[70:71], v[70:71], v[144:145], v[146:147]
	v_lshlrev_b32_e32 v146, 16, v189
	v_and_b32_e32 v147, 0xffff0000, v189
	v_lshlrev_b32_e32 v144, 16, v205
	v_and_b32_e32 v145, 0xffff0000, v205
	v_pk_fma_f32 v[72:73], v[72:73], v[144:145], v[146:147]
	v_lshlrev_b32_e32 v146, 16, v190
	v_and_b32_e32 v147, 0xffff0000, v190
	v_lshlrev_b32_e32 v144, 16, v206
	v_and_b32_e32 v145, 0xffff0000, v206
	v_pk_fma_f32 v[66:67], v[66:67], v[144:145], v[146:147]
	v_lshlrev_b32_e32 v146, 16, v191
	v_and_b32_e32 v147, 0xffff0000, v191
	v_lshlrev_b32_e32 v144, 16, v207
	v_and_b32_e32 v145, 0xffff0000, v207
	v_pk_fma_f32 v[68:69], v[68:69], v[144:145], v[146:147]
	global_load_dwordx4 v[176:179], v[152:153], off
	global_load_dwordx4 v[192:195], v[154:155], off
	global_load_dwordx4 v[180:183], v[152:153], off offset:256
	global_load_dwordx4 v[196:199], v[154:155], off offset:256
	v_lshl_add_u64 v[152:153], v[152:153], 0, s[16:17]
	v_lshl_add_u64 v[154:155], v[154:155], 0, s[16:17]
	global_load_dwordx4 v[184:187], v[152:153], off
	global_load_dwordx4 v[200:203], v[154:155], off
	global_load_dwordx4 v[188:191], v[152:153], off offset:256
	global_load_dwordx4 v[204:207], v[154:155], off offset:256
	v_lshl_add_u64 v[152:153], v[152:153], 0, s[16:17]
	v_lshl_add_u64 v[154:155], v[154:155], 0, s[16:17]
	v_cvt_pk_bf16_f32 v172, v94, v95
	v_cvt_pk_bf16_f32 v173, v96, v97
	v_cvt_pk_bf16_f32 v174, v90, v91
	v_cvt_pk_bf16_f32 v175, v92, v93
	global_store_dwordx4 v[150:151], v[172:175], off
	v_cvt_pk_bf16_f32 v156, v86, v87
	v_cvt_pk_bf16_f32 v157, v88, v89
	v_cvt_pk_bf16_f32 v158, v82, v83
	v_cvt_pk_bf16_f32 v159, v84, v85
	global_store_dwordx4 v[150:151], v[156:159], off offset:256
	v_lshl_add_u64 v[150:151], v[150:151], 0, s[16:17]
	v_cvt_pk_bf16_f32 v172, v78, v79
	v_cvt_pk_bf16_f32 v173, v80, v81
	v_cvt_pk_bf16_f32 v174, v74, v75
	v_cvt_pk_bf16_f32 v175, v76, v77
	global_store_dwordx4 v[150:151], v[172:175], off
	v_cvt_pk_bf16_f32 v156, v70, v71
	v_cvt_pk_bf16_f32 v157, v72, v73
	v_cvt_pk_bf16_f32 v158, v66, v67
	v_cvt_pk_bf16_f32 v159, v68, v69
	global_store_dwordx4 v[150:151], v[156:159], off offset:256
	v_lshl_add_u64 v[150:151], v[150:151], 0, s[30:31]
	s_waitcnt vmcnt(4)
; __device__ __forceinline__ unsigned cvt_pk_bf16(float lo, float hi) { unsigned r; asm volatile("v_cvt_pk_bf16_f32 %0, %1, %2" : "=v"(r) : "v"(lo), "v"(hi)); return r; }
; __device__ __forceinline__ float bflo(unsigned w) { return __uint_as_float(w << 16); }
; __device__ __forceinline__ float bfhi(unsigned w) { return __uint_as_float(w & 0xffff0000u); }
; __device__ __forceinline__ float bflo(unsigned w) { return __uint_as_float(w << 16); }
; __device__ __forceinline__ float bfhi(unsigned w) { return __uint_as_float(w & 0xffff0000u); }
;     __device__ __forceinline__ void operator()(const f32x4 (&acc)[2][2][4][2], const Unit& u, int wr, int wc, int fr, int fq) const {
;     ...
;                         } else {
;                             const u32x4e y = *(const u32x4e*)(aux1 + off); const u32x4e g = *(const u32x4e*)(aux2 + off);
;                             v0[0] = bflo(y.x) + bflo(g.x) * v0[0]; v0[1] = bfhi(y.x) + bfhi(g.x) * v0[1]; v0[2] = bflo(y.y) + bflo(g.y) * v0[2]; v0[3] = bfhi(y.y) + bfhi(g.y) * v0[3];
;                             v1[0] = bflo(y.z) + bflo(g.z) * v1[0]; v1[1] = bfhi(y.z) + bfhi(g.z) * v1[1]; v1[2] = bflo(y.w) + bflo(g.w) * v1[2]; v1[3] = bfhi(y.w) + bfhi(g.w) * v1[3];
;                         }
;                         u32x4e w; w.x = cvt_pk_bf16(v0[0], v0[1]); w.y = cvt_pk_bf16(v0[2], v0[3]); w.z = cvt_pk_bf16(v1[0], v1[1]); w.w = cvt_pk_bf16(v1[2], v1[3]);
;                         *(u32x4e*)(base + off) = w;
	v_lshlrev_b32_e32 v146, 16, v176
	v_and_b32_e32 v147, 0xffff0000, v176
	v_lshlrev_b32_e32 v144, 16, v192
	v_and_b32_e32 v145, 0xffff0000, v192
	v_pk_fma_f32 v[60:61], v[60:61], v[144:145], v[146:147]
	v_lshlrev_b32_e32 v146, 16, v177
	v_and_b32_e32 v147, 0xffff0000, v177
	v_lshlrev_b32_e32 v144, 16, v193
	v_and_b32_e32 v145, 0xffff0000, v193
	v_pk_fma_f32 v[62:63], v[62:63], v[144:145], v[146:147]
	v_lshlrev_b32_e32 v146, 16, v178
	v_and_b32_e32 v147, 0xffff0000, v178
	v_lshlrev_b32_e32 v144, 16, v194
	v_and_b32_e32 v145, 0xffff0000, v194
	v_pk_fma_f32 v[56:57], v[56:57], v[144:145], v[146:147]
	v_lshlrev_b32_e32 v146, 16, v179
	v_and_b32_e32 v147, 0xffff0000, v179
	v_lshlrev_b32_e32 v144, 16, v195
	v_and_b32_e32 v145, 0xffff0000, v195
	v_pk_fma_f32 v[58:59], v[58:59], v[144:145], v[146:147]
	v_lshlrev_b32_e32 v146, 16, v180
	v_and_b32_e32 v147, 0xffff0000, v180
	v_lshlrev_b32_e32 v144, 16, v196
	v_and_b32_e32 v145, 0xffff0000, v196
	v_pk_fma_f32 v[52:53], v[52:53], v[144:145], v[146:147]
	v_lshlrev_b32_e32 v146, 16, v181
	v_and_b32_e32 v147, 0xffff0000, v181
	v_lshlrev_b32_e32 v144, 16, v197
	v_and_b32_e32 v145, 0xffff0000, v197
	v_pk_fma_f32 v[54:55], v[54:55], v[144:145], v[146:147]
	v_lshlrev_b32_e32 v146, 16, v182
	v_and_b32_e32 v147, 0xffff0000, v182
	v_lshlrev_b32_e32 v144, 16, v198
	v_and_b32_e32 v145, 0xffff0000, v198
	v_pk_fma_f32 v[48:49], v[48:49], v[144:145], v[146:147]
	v_lshlrev_b32_e32 v146, 16, v183
	v_and_b32_e32 v147, 0xffff0000, v183
	v_lshlrev_b32_e32 v144, 16, v199
	v_and_b32_e32 v145, 0xffff0000, v199
	v_pk_fma_f32 v[50:51], v[50:51], v[144:145], v[146:147]
	v_lshlrev_b32_e32 v146, 16, v184
	v_and_b32_e32 v147, 0xffff0000, v184
	v_lshlrev_b32_e32 v144, 16, v200
	v_and_b32_e32 v145, 0xffff0000, v200
	v_pk_fma_f32 v[44:45], v[44:45], v[144:145], v[146:147]
	v_lshlrev_b32_e32 v146, 16, v185
	v_and_b32_e32 v147, 0xffff0000, v185
	v_lshlrev_b32_e32 v144, 16, v201
	v_and_b32_e32 v145, 0xffff0000, v201
	v_pk_fma_f32 v[46:47], v[46:47], v[144:145], v[146:147]
	v_lshlrev_b32_e32 v146, 16, v186
	v_and_b32_e32 v147, 0xffff0000, v186
	v_lshlrev_b32_e32 v144, 16, v202
	v_and_b32_e32 v145, 0xffff0000, v202
	v_pk_fma_f32 v[40:41], v[40:41], v[144:145], v[146:147]
	v_lshlrev_b32_e32 v146, 16, v187
	v_and_b32_e32 v147, 0xffff0000, v187
	v_lshlrev_b32_e32 v144, 16, v203
	v_and_b32_e32 v145, 0xffff0000, v203
	v_pk_fma_f32 v[42:43], v[42:43], v[144:145], v[146:147]
	v_lshlrev_b32_e32 v146, 16, v188
	v_and_b32_e32 v147, 0xffff0000, v188
	v_lshlrev_b32_e32 v144, 16, v204
	v_and_b32_e32 v145, 0xffff0000, v204
	v_pk_fma_f32 v[36:37], v[36:37], v[144:145], v[146:147]
	v_lshlrev_b32_e32 v146, 16, v189
	v_and_b32_e32 v147, 0xffff0000, v189
	v_lshlrev_b32_e32 v144, 16, v205
	v_and_b32_e32 v145, 0xffff0000, v205
	v_pk_fma_f32 v[38:39], v[38:39], v[144:145], v[146:147]
	v_lshlrev_b32_e32 v146, 16, v190
	v_and_b32_e32 v147, 0xffff0000, v190
	v_lshlrev_b32_e32 v144, 16, v206
	v_and_b32_e32 v145, 0xffff0000, v206
	v_pk_fma_f32 v[32:33], v[32:33], v[144:145], v[146:147]
	v_lshlrev_b32_e32 v146, 16, v191
	v_and_b32_e32 v147, 0xffff0000, v191
	v_lshlrev_b32_e32 v144, 16, v207
	v_and_b32_e32 v145, 0xffff0000, v207
	v_pk_fma_f32 v[34:35], v[34:35], v[144:145], v[146:147]
	global_load_dwordx4 v[176:179], v[152:153], off
	global_load_dwordx4 v[192:195], v[154:155], off
	global_load_dwordx4 v[180:183], v[152:153], off offset:256
	global_load_dwordx4 v[196:199], v[154:155], off offset:256
	v_lshl_add_u64 v[152:153], v[152:153], 0, s[16:17]
	v_lshl_add_u64 v[154:155], v[154:155], 0, s[16:17]
	global_load_dwordx4 v[184:187], v[152:153], off
	global_load_dwordx4 v[200:203], v[154:155], off
	global_load_dwordx4 v[188:191], v[152:153], off offset:256
	global_load_dwordx4 v[204:207], v[154:155], off offset:256
	v_cvt_pk_bf16_f32 v172, v60, v61
	v_cvt_pk_bf16_f32 v173, v62, v63
	v_cvt_pk_bf16_f32 v174, v56, v57
	v_cvt_pk_bf16_f32 v175, v58, v59
	global_store_dwordx4 v[150:151], v[172:175], off
	v_cvt_pk_bf16_f32 v156, v52, v53
	v_cvt_pk_bf16_f32 v157, v54, v55
	v_cvt_pk_bf16_f32 v158, v48, v49
	v_cvt_pk_bf16_f32 v159, v50, v51
	global_store_dwordx4 v[150:151], v[156:159], off offset:256
	v_lshl_add_u64 v[150:151], v[150:151], 0, s[16:17]
	v_cvt_pk_bf16_f32 v172, v44, v45
	v_cvt_pk_bf16_f32 v173, v46, v47
	v_cvt_pk_bf16_f32 v174, v40, v41
	v_cvt_pk_bf16_f32 v175, v42, v43
	global_store_dwordx4 v[150:151], v[172:175], off
	v_cvt_pk_bf16_f32 v156, v36, v37
	v_cvt_pk_bf16_f32 v157, v38, v39
	v_cvt_pk_bf16_f32 v158, v32, v33
	v_cvt_pk_bf16_f32 v159, v34, v35
	global_store_dwordx4 v[150:151], v[156:159], off offset:256
	v_lshl_add_u64 v[150:151], v[150:151], 0, s[16:17]
	s_waitcnt vmcnt(4)
; __device__ __forceinline__ unsigned cvt_pk_bf16(float lo, float hi) { unsigned r; asm volatile("v_cvt_pk_bf16_f32 %0, %1, %2" : "=v"(r) : "v"(lo), "v"(hi)); return r; }
; __device__ __forceinline__ float bflo(unsigned w) { return __uint_as_float(w << 16); }
; __device__ __forceinline__ float bfhi(unsigned w) { return __uint_as_float(w & 0xffff0000u); }
; __device__ __forceinline__ float bflo(unsigned w) { return __uint_as_float(w << 16); }
; __device__ __forceinline__ float bfhi(unsigned w) { return __uint_as_float(w & 0xffff0000u); }
;     __device__ __forceinline__ void operator()(const f32x4 (&acc)[2][2][4][2], const Unit& u, int wr, int wc, int fr, int fq) const {
;     ...
;                         } else {
;                             const u32x4e y = *(const u32x4e*)(aux1 + off); const u32x4e g = *(const u32x4e*)(aux2 + off);
;                             v0[0] = bflo(y.x) + bflo(g.x) * v0[0]; v0[1] = bfhi(y.x) + bfhi(g.x) * v0[1]; v0[2] = bflo(y.y) + bflo(g.y) * v0[2]; v0[3] = bfhi(y.y) + bfhi(g.y) * v0[3];
;                             v1[0] = bflo(y.z) + bflo(g.z) * v1[0]; v1[1] = bfhi(y.z) + bfhi(g.z) * v1[1]; v1[2] = bflo(y.w) + bflo(g.w) * v1[2]; v1[3] = bfhi(y.w) + bfhi(g.w) * v1[3];
;                         }
;                         u32x4e w; w.x = cvt_pk_bf16(v0[0], v0[1]); w.y = cvt_pk_bf16(v0[2], v0[3]); w.z = cvt_pk_bf16(v1[0], v1[1]); w.w = cvt_pk_bf16(v1[2], v1[3]);
;                         *(u32x4e*)(base + off) = w;
	v_lshlrev_b32_e32 v146, 16, v176
	v_and_b32_e32 v147, 0xffff0000, v176
	v_lshlrev_b32_e32 v144, 16, v192
	v_and_b32_e32 v145, 0xffff0000, v192
	v_pk_fma_f32 v[28:29], v[28:29], v[144:145], v[146:147]
	v_lshlrev_b32_e32 v146, 16, v177
	v_and_b32_e32 v147, 0xffff0000, v177
	v_lshlrev_b32_e32 v144, 16, v193
	v_and_b32_e32 v145, 0xffff0000, v193
	v_pk_fma_f32 v[30:31], v[30:31], v[144:145], v[146:147]
	v_lshlrev_b32_e32 v146, 16, v178
	v_and_b32_e32 v147, 0xffff0000, v178
	v_lshlrev_b32_e32 v144, 16, v194
	v_and_b32_e32 v145, 0xffff0000, v194
	v_pk_fma_f32 v[24:25], v[24:25], v[144:145], v[146:147]
	v_lshlrev_b32_e32 v146, 16, v179
	v_and_b32_e32 v147, 0xffff0000, v179
	v_lshlrev_b32_e32 v144, 16, v195
	v_and_b32_e32 v145, 0xffff0000, v195
	v_pk_fma_f32 v[26:27], v[26:27], v[144:145], v[146:147]
	v_lshlrev_b32_e32 v146, 16, v180
	v_and_b32_e32 v147, 0xffff0000, v180
	v_lshlrev_b32_e32 v144, 16, v196
	v_and_b32_e32 v145, 0xffff0000, v196
	v_pk_fma_f32 v[20:21], v[20:21], v[144:145], v[146:147]
	v_lshlrev_b32_e32 v146, 16, v181
	v_and_b32_e32 v147, 0xffff0000, v181
	v_lshlrev_b32_e32 v144, 16, v197
	v_and_b32_e32 v145, 0xffff0000, v197
	v_pk_fma_f32 v[22:23], v[22:23], v[144:145], v[146:147]
	v_lshlrev_b32_e32 v146, 16, v182
	v_and_b32_e32 v147, 0xffff0000, v182
	v_lshlrev_b32_e32 v144, 16, v198
	v_and_b32_e32 v145, 0xffff0000, v198
	v_pk_fma_f32 v[16:17], v[16:17], v[144:145], v[146:147]
	v_lshlrev_b32_e32 v146, 16, v183
	v_and_b32_e32 v147, 0xffff0000, v183
	v_lshlrev_b32_e32 v144, 16, v199
	v_and_b32_e32 v145, 0xffff0000, v199
	v_pk_fma_f32 v[18:19], v[18:19], v[144:145], v[146:147]
	v_lshlrev_b32_e32 v146, 16, v184
	v_and_b32_e32 v147, 0xffff0000, v184
	v_lshlrev_b32_e32 v144, 16, v200
	v_and_b32_e32 v145, 0xffff0000, v200
	v_pk_fma_f32 v[12:13], v[12:13], v[144:145], v[146:147]
	v_lshlrev_b32_e32 v146, 16, v185
	v_and_b32_e32 v147, 0xffff0000, v185
	v_lshlrev_b32_e32 v144, 16, v201
	v_and_b32_e32 v145, 0xffff0000, v201
	v_pk_fma_f32 v[14:15], v[14:15], v[144:145], v[146:147]
	v_lshlrev_b32_e32 v146, 16, v186
	v_and_b32_e32 v147, 0xffff0000, v186
	v_lshlrev_b32_e32 v144, 16, v202
	v_and_b32_e32 v145, 0xffff0000, v202
	v_pk_fma_f32 v[8:9], v[8:9], v[144:145], v[146:147]
	v_lshlrev_b32_e32 v146, 16, v187
	v_and_b32_e32 v147, 0xffff0000, v187
	v_lshlrev_b32_e32 v144, 16, v203
	v_and_b32_e32 v145, 0xffff0000, v203
	v_pk_fma_f32 v[10:11], v[10:11], v[144:145], v[146:147]
	v_lshlrev_b32_e32 v146, 16, v188
	v_and_b32_e32 v147, 0xffff0000, v188
	v_lshlrev_b32_e32 v144, 16, v204
	v_and_b32_e32 v145, 0xffff0000, v204
	v_pk_fma_f32 v[4:5], v[4:5], v[144:145], v[146:147]
	v_lshlrev_b32_e32 v146, 16, v189
	v_and_b32_e32 v147, 0xffff0000, v189
	v_lshlrev_b32_e32 v144, 16, v205
	v_and_b32_e32 v145, 0xffff0000, v205
	v_pk_fma_f32 v[6:7], v[6:7], v[144:145], v[146:147]
	v_lshlrev_b32_e32 v146, 16, v190
	v_and_b32_e32 v147, 0xffff0000, v190
	v_lshlrev_b32_e32 v144, 16, v206
	v_and_b32_e32 v145, 0xffff0000, v206
	v_pk_fma_f32 v[0:1], v[0:1], v[144:145], v[146:147]
	v_lshlrev_b32_e32 v146, 16, v191
	v_and_b32_e32 v147, 0xffff0000, v191
	v_lshlrev_b32_e32 v144, 16, v207
	v_and_b32_e32 v145, 0xffff0000, v207
	v_pk_fma_f32 v[2:3], v[2:3], v[144:145], v[146:147]
	v_cvt_pk_bf16_f32 v172, v28, v29
	v_cvt_pk_bf16_f32 v173, v30, v31
	v_cvt_pk_bf16_f32 v174, v24, v25
	v_cvt_pk_bf16_f32 v175, v26, v27
	global_store_dwordx4 v[150:151], v[172:175], off
	v_cvt_pk_bf16_f32 v156, v20, v21
	v_cvt_pk_bf16_f32 v157, v22, v23
	v_cvt_pk_bf16_f32 v158, v16, v17
	v_cvt_pk_bf16_f32 v159, v18, v19
	global_store_dwordx4 v[150:151], v[156:159], off offset:256
	v_lshl_add_u64 v[150:151], v[150:151], 0, s[16:17]
	v_cvt_pk_bf16_f32 v172, v12, v13
	v_cvt_pk_bf16_f32 v173, v14, v15
	v_cvt_pk_bf16_f32 v174, v8, v9
	v_cvt_pk_bf16_f32 v175, v10, v11
	global_store_dwordx4 v[150:151], v[172:175], off
	v_cvt_pk_bf16_f32 v156, v4, v5
	v_cvt_pk_bf16_f32 v157, v6, v7
	v_cvt_pk_bf16_f32 v158, v0, v1
	v_cvt_pk_bf16_f32 v159, v2, v3
	global_store_dwordx4 v[150:151], v[156:159], off offset:256
	s_branch .LBB0_967
